# code placement: hot loop heads (5 GEMM K-loops, attention inner loop, P0 x loop) aligned to 64-byte instruction-cache lines
# speedup vs baseline: 1.0040x; 1.0027x over previous
; #define GAS __attribute__((address_space(1)))
; __global__ void __launch_bounds__(NWAVES * 64, 2) mk_fwd(Args args) {
;     ...
;         for (int m = gw; m < M; m += 2 * NGW) {
;             const int m1 = m + NGW;
;             const bool has1 = m1 < M;
;             const GAS f32x4* xr0 = (const GAS f32x4*)(x + (size_t)m * DM) + lane;
;             const GAS f32x4* xr1 = (const GAS f32x4*)(x + (size_t)(has1 ? m1 : m) * DM) + lane;
;             f32x4 v0[4], v1[4]; float s0 = 0.f, s1 = 0.f;
; #pragma unroll
;             for (int j = 0; j < 4; ++j) { v0[j] = xr0[64 * j]; v1[j] = xr1[64 * j]; }
.LBB0_44:
	s_add_i32 s8, s6, s55
	s_cmpk_lt_i32 s8, 0x4000
	s_cbranch_scc0 .LBB0_50
	.p2align 6

; #define PG8_WAIT_V(n) asm volatile("s_waitcnt vmcnt(" #n ")" ::: "memory")
; #define PG8_BAR __builtin_amdgcn_s_barrier()
; template <class Epi, class Sched, bool ALIGN_EPI = false, bool SP2 = false>
; __device__ __forceinline__ void gemm_phase(PG8_LAS unsigned char* lds, const Gemm g, const Sched& S, const Epi& E) {
;     ...
;     f32x4 acc[2][2][4][2];
; #pragma unroll
;     for (int a = 0; a < 2; ++a)
; #pragma unroll
;         for (int b = 0; b < 2; ++b)
; #pragma unroll
;             for (int m = 0; m < 4; ++m)
; #pragma unroll
;                 for (int n = 0; n < 2; ++n) acc[a][b][m][n] = (f32x4){0.f, 0.f, 0.f, 0.f};
;     bf16x8 At[4][2], B0[2][2], B1[2][2];
;     const char* cA = (const char*)g.A + (size_t)cur.pm * tstep + (size_t)cur.seg * K * 2; const char* cB = (const char*)g.Bt + (size_t)cur.pn * tstepB + (size_t)cur.seg * K * 2;
;     if constexpr (SP2) {
;         PG8_STAGE(PG8_SB(0, 0), cB, voffB); PG8_STAGE(PG8_SB(0, 1), cB + hstepB, voffB); PG8_STAGE(PG8_SA(0, 0), cA, voffA); PG8_STAGE(PG8_SA(0, 1), cA + hstep, voffA);
;         if (wr == 1) PG8_BAR;
;         PG8_WAIT_V(2); PG8_BAR;
;         PG8_STAGE(PG8_SB(1, 0), cB + kstep, voffB); PG8_STAGE(PG8_SA(1, 0), cA + kstep, voffA); PG8_STAGE(PG8_SB(1, 1), cB + hstepB + kstep, voffB);
;         PG8_WAIT_V(6); PG8_BAR;
;     } else {
;         PG8_STAGE(PG8_SB(0, 0), cB, voffB); PG8_STAGE(PG8_SA(0, 0), cA, voffA); PG8_STAGE(PG8_SB(0, 1), cB + hstepB, voffB); PG8_STAGE(PG8_SA(0, 1), cA + hstep, voffA);
;         if (wr == 1) PG8_BAR;
;         PG8_WAIT_V(4); PG8_BAR;
;         PG8_STAGE(PG8_SB(1, 0), cB + kstep, voffB); PG8_STAGE(PG8_SA(1, 0), cA + kstep, voffA); PG8_STAGE(PG8_SB(1, 1), cB + hstepB + kstep, voffB);
;         PG8_WAIT_V(6); PG8_BAR;
;     }
;     for (;;) {
;         const bool has_next = S.next(ui + 1, nxt);
;         const char* nA = has_next ? (const char*)g.A + (size_t)nxt.pm * tstep + (size_t)nxt.seg * K * 2 : cA; const char* nB = has_next ? (const char*)g.Bt + (size_t)nxt.pn * tstepB + (size_t)nxt.seg * K * 2 : cB;
;         for (int t = 0; t < nt; t += 2) {
;             const bool last = (t == nt - 2);
;             const char* a1 = cA + (size_t)(t + 1) * kstep;
;             const char* a2 = last ? nA : cA + (size_t)(t + 2) * kstep; const char* b2 = last ? nB : cB + (size_t)(t + 2) * kstep;
;             const char* a3 = a2 + kstep; const char* b3 = b2 + kstep;
.LBB0_129:
	s_ashr_i32 s49, s48, 31
	s_lshl_b64 s[30:31], s[48:49], 19
	s_add_u32 s70, s90, s30
	s_addc_u32 s71, s91, s31
	s_and_b64 s[30:31], s[66:67], exec
	s_cselect_b32 s49, s71, s37
	s_cselect_b32 s77, s70, s36
	s_ashr_i32 s51, s50, 31
	s_lshl_b64 s[30:31], s[50:51], 19
	s_add_u32 s72, s42, s30
	s_addc_u32 s73, s43, s31
	s_and_b64 s[30:31], s[66:67], exec
	s_cselect_b32 s51, s73, s39
	s_cselect_b32 vcc_lo, s72, s38
	s_add_u32 s36, s36, 0x40080
	s_addc_u32 s37, s37, 0
	s_add_u32 vcc_hi, s38, 0x100
	v_mov_b32_e32 v2, 0
	s_addc_u32 s30, s39, 0
	s_mov_b32 s31, -2
	v_mov_b32_e32 v3, v2
	v_mov_b32_e32 v4, v2
	v_mov_b32_e32 v5, v2
	v_mov_b32_e32 v6, v2
	v_mov_b32_e32 v7, v2
	v_mov_b32_e32 v8, v2
	v_mov_b32_e32 v9, v2
	v_mov_b32_e32 v18, v2
	v_mov_b32_e32 v19, v2
	s_waitcnt lgkmcnt(0)
	v_mov_b32_e32 v20, v2
	v_mov_b32_e32 v21, v2
	v_mov_b32_e32 v22, v2
	v_mov_b32_e32 v23, v2
	v_mov_b32_e32 v24, v2
	v_mov_b32_e32 v25, v2
	v_mov_b32_e32 v34, v2
	v_mov_b32_e32 v35, v2
	v_mov_b32_e32 v36, v2
	v_mov_b32_e32 v37, v2
	v_mov_b32_e32 v38, v2
	v_mov_b32_e32 v39, v2
	v_mov_b32_e32 v40, v2
	v_mov_b32_e32 v41, v2
	v_mov_b32_e32 v50, v2
	v_mov_b32_e32 v51, v2
	v_mov_b32_e32 v52, v2
	v_mov_b32_e32 v53, v2
	v_mov_b32_e32 v54, v2
	v_mov_b32_e32 v55, v2
	v_mov_b32_e32 v56, v2
	v_mov_b32_e32 v57, v2
	v_mov_b32_e32 v10, v2
	v_mov_b32_e32 v11, v2
	v_mov_b32_e32 v12, v2
	v_mov_b32_e32 v13, v2
	v_mov_b32_e32 v14, v2
	v_mov_b32_e32 v15, v2
	v_mov_b32_e32 v16, v2
	v_mov_b32_e32 v17, v2
	v_mov_b32_e32 v26, v2
	v_mov_b32_e32 v27, v2
	v_mov_b32_e32 v28, v2
	v_mov_b32_e32 v29, v2
	v_mov_b32_e32 v30, v2
	v_mov_b32_e32 v31, v2
	v_mov_b32_e32 v32, v2
	v_mov_b32_e32 v33, v2
	v_mov_b32_e32 v42, v2
	v_mov_b32_e32 v43, v2
	v_mov_b32_e32 v44, v2
	v_mov_b32_e32 v45, v2
	v_mov_b32_e32 v46, v2
	v_mov_b32_e32 v47, v2
	v_mov_b32_e32 v48, v2
	v_mov_b32_e32 v49, v2
	v_mov_b32_e32 v58, v2
	v_mov_b32_e32 v59, v2
	v_mov_b32_e32 v60, v2
	v_mov_b32_e32 v61, v2
	v_mov_b32_e32 v62, v2
	v_mov_b32_e32 v63, v2
	v_mov_b32_e32 v64, v2
	v_mov_b32_e32 v65, v2
	v_mov_b32_e32 v68, v2
	v_mov_b32_e32 v69, v2
	v_mov_b32_e32 v70, v2
	v_mov_b32_e32 v71, v2
	v_mov_b32_e32 v72, v2
	v_mov_b32_e32 v73, v2
	v_mov_b32_e32 v74, v2
	v_mov_b32_e32 v75, v2
	v_mov_b32_e32 v84, v2
	v_mov_b32_e32 v85, v2
	v_mov_b32_e32 v86, v2
	v_mov_b32_e32 v87, v2
	v_mov_b32_e32 v88, v2
	v_mov_b32_e32 v89, v2
	v_mov_b32_e32 v90, v2
	v_mov_b32_e32 v91, v2
	v_mov_b32_e32 v100, v2
	v_mov_b32_e32 v101, v2
	v_mov_b32_e32 v102, v2
	v_mov_b32_e32 v103, v2
	v_mov_b32_e32 v104, v2
	v_mov_b32_e32 v105, v2
	v_mov_b32_e32 v106, v2
	v_mov_b32_e32 v107, v2
	v_mov_b32_e32 v116, v2
	v_mov_b32_e32 v117, v2
	v_mov_b32_e32 v118, v2
	v_mov_b32_e32 v119, v2
	v_mov_b32_e32 v120, v2
	v_mov_b32_e32 v121, v2
	v_mov_b32_e32 v122, v2
	v_mov_b32_e32 v123, v2
	v_mov_b32_e32 v76, v2
	v_mov_b32_e32 v77, v2
	v_mov_b32_e32 v78, v2
	v_mov_b32_e32 v79, v2
	v_mov_b32_e32 v80, v2
	v_mov_b32_e32 v81, v2
	v_mov_b32_e32 v82, v2
	v_mov_b32_e32 v83, v2
	v_mov_b32_e32 v92, v2
	v_mov_b32_e32 v93, v2
	v_mov_b32_e32 v94, v2
	v_mov_b32_e32 v95, v2
	v_mov_b32_e32 v96, v2
	v_mov_b32_e32 v97, v2
	v_mov_b32_e32 v98, v2
	v_mov_b32_e32 v99, v2
	v_mov_b32_e32 v108, v2
	v_mov_b32_e32 v109, v2
	v_mov_b32_e32 v110, v2
	v_mov_b32_e32 v111, v2
	v_mov_b32_e32 v112, v2
	v_mov_b32_e32 v113, v2
	v_mov_b32_e32 v114, v2
	v_mov_b32_e32 v115, v2
	v_mov_b32_e32 v124, v2
	v_mov_b32_e32 v125, v2
	v_mov_b32_e32 v126, v2
	v_mov_b32_e32 v127, v2
	v_mov_b32_e32 v128, v2
	v_mov_b32_e32 v129, v2
	v_mov_b32_e32 v130, v2
	v_mov_b32_e32 v131, v2
	.p2align 6

; #define ATT_QK(dst, cblk) do { _Pragma("unroll") for (int r = 0; r < 16; ++r) dst[r] = 0.f; \
;             _Pragma("unroll") for (int ks = 0; ks < 4; ++ks) { const bf16x8 kf = *(const LAS bf16x8*)(Ks + ((cblk) + r32) * KS_PITCH + ks * 16 + hi * 8); \
;                 dst = __builtin_amdgcn_mfma_f32_32x32x16_bf16(kf, qf[ks], dst, 0, 0, 0); } } while (0)
; __device__ __forceinline__ void attn_unit(LAS unsigned char* lds, const bf16* PROJ, bf16* DA, const float* sinkl, int unit, int tid, int wid, int lane) {
;     ...
;         const int a0 = 64 * (wid & 1) + 32 * sb, a = a0 + r32;
;         const size_t qrow = rowb + (size_t)n * 128 + a;
;         bf16x8 qf[4];
; #pragma unroll
;         for (int ks = 0; ks < 4; ++ks) qf[ks] = *(const bf16x8*)(PROJ + qrow * INW + 512 + hq * 64 + ks * 16 + hi * 8);
;         float mrun = sink2, l = 0.f;
;         f32x16 o0, o1;
; #pragma unroll
;         for (int r = 0; r < 16; ++r) { o0[r] = 0.f; o1[r] = 0.f; }
;         const float fb0 = (float)(r32 + 128 - 4 * hi);
;         f32x16 pn;
;     ...
;         ATT_QK(pn, a0);
; #pragma unroll 1
;         for (int i = 0; i < 9; ++i) {
.Lq_skip1:
	v_mad_u32_u24 v26, v4, s3, v84
	ds_read_b128 v[18:21], v26
	ds_read_b128 v[22:25], v26 offset:32
	s_mov_b32 s37, s36
	s_xor_b64 s[70:71], s[38:39], -1
	s_mov_b32 s38, s36
	s_mov_b32 s39, s36
	s_mov_b32 s40, s36
	s_mov_b32 s41, s36
	s_mov_b32 s42, s36
	s_mov_b32 s43, s36
	s_mov_b32 s44, s36
	s_mov_b32 s45, s36
	s_mov_b32 s46, s36
	s_mov_b32 s47, s36
	s_mov_b32 s48, s36
	s_mov_b32 s49, s36
	s_mov_b32 s50, s36
	s_mov_b32 s51, s36
	v_mov_b64_e32 v[2:3], s[36:37]
	v_mov_b64_e32 v[16:17], s[50:51]
	s_lshl_b32 s24, s23, 1
	v_mov_b64_e32 v[4:5], s[38:39]
	v_mov_b64_e32 v[6:7], s[40:41]
	v_mov_b64_e32 v[8:9], s[42:43]
	v_mov_b64_e32 v[10:11], s[44:45]
	v_mov_b64_e32 v[12:13], s[46:47]
	v_mov_b64_e32 v[14:15], s[48:49]
	v_add_u32_e32 v100, s24, v96
	v_add_u32_e32 v101, s24, v97
	v_mov_b32_e32 v91, s7
	v_subrev_u32_e32 v102, s23, v98
	v_mov_b32_e32 v103, v94
	s_waitcnt vmcnt(3) lgkmcnt(1)
	v_mfma_f32_32x32x16_bf16 v[50:65], v[18:21], v[68:71], v[34:49]
	ds_read_b128 v[18:21], v26 offset:64
	s_waitcnt vmcnt(2) lgkmcnt(1)
	v_mfma_f32_32x32x16_bf16 v[50:65], v[22:25], v[72:75], v[50:65]
	s_waitcnt vmcnt(1) lgkmcnt(0)
	v_mfma_f32_32x32x16_bf16 v[50:65], v[18:21], v[76:79], v[50:65]
	ds_read_b128 v[18:21], v26 offset:96
	s_waitcnt vmcnt(0) lgkmcnt(0)
	v_mfma_f32_32x32x16_bf16 v[50:65], v[18:21], v[80:83], v[50:65]
	v_add_u32_e32 v18, s23, v99
	v_mad_u64_u32 v[92:93], s[24:25], v18, s3, v[84:85]
	v_mov_b64_e32 v[32:33], v[16:17]
	v_mov_b32_e32 v93, 0
	s_mov_b32 s23, 0
	s_mov_b32 s24, 0
	s_nop 5
	v_mov_b64_e32 v[30:31], v[14:15]
	v_mov_b64_e32 v[28:29], v[12:13]
	v_mov_b64_e32 v[26:27], v[10:11]
	v_mov_b64_e32 v[24:25], v[8:9]
	v_mov_b64_e32 v[22:23], v[6:7]
	v_mov_b64_e32 v[20:21], v[4:5]
	v_mov_b64_e32 v[18:19], v[2:3]
	.p2align 6

; template <class Epi, class Sched, bool ALIGN_EPI = false, bool SP2 = false>
; __device__ __forceinline__ void gemm_phase(PG8_LAS unsigned char* lds, const Gemm g, const Sched& S, const Epi& E) {
;     ...
;         const bool has_next = S.next(ui + 1, nxt);
;         const char* nA = has_next ? (const char*)g.A + (size_t)nxt.pm * tstep + (size_t)nxt.seg * K * 2 : cA; const char* nB = has_next ? (const char*)g.Bt + (size_t)nxt.pn * tstepB + (size_t)nxt.seg * K * 2 : cB;
;         for (int t = 0; t < nt; t += 2) {
;             const bool last = (t == nt - 2);
;             const char* a1 = cA + (size_t)(t + 1) * kstep;
;             const char* a2 = last ? nA : cA + (size_t)(t + 2) * kstep; const char* b2 = last ? nB : cB + (size_t)(t + 2) * kstep;
;             const char* a3 = a2 + kstep; const char* b3 = b2 + kstep;
.LBB0_515:
	s_ashr_i32 s47, s46, 31
	s_and_b32 s26, s25, 1
	s_lshl_b64 s[30:31], s[46:47], 19
	s_add_u32 s30, s68, s30
	s_addc_u32 s31, s69, s31
	s_lshl_b32 s34, s26, 10
	s_add_u32 s50, s30, s34
	s_addc_u32 s51, s31, 0
	s_and_b64 s[30:31], s[70:71], exec
	s_cselect_b32 s37, s51, s39
	s_cselect_b32 s47, s50, s38
	s_ashr_i32 s49, s48, 31
	s_lshl_b64 s[30:31], s[48:49], 19
	s_add_u32 s30, s56, s30
	s_addc_u32 s31, s57, s31
	s_add_u32 s66, s30, s34
	s_addc_u32 s67, s31, 0
	s_and_b64 s[30:31], s[70:71], exec
	s_cselect_b32 s49, s67, s73
	s_cselect_b32 vcc_lo, s66, s72
	s_add_u32 s38, s38, 0x40080
	s_addc_u32 s39, s39, 0
	s_add_u32 s30, s72, 0x100
	s_addc_u32 s31, s73, 0
	s_mov_b32 vcc_hi, -2
	.p2align 6

; #define PG8_WAIT_V(n) asm volatile("s_waitcnt vmcnt(" #n ")" ::: "memory")
; #define PG8_BAR __builtin_amdgcn_s_barrier()
; template <class Epi, class Sched, bool ALIGN_EPI = false, bool SP2 = false>
; __device__ __forceinline__ void gemm_phase(PG8_LAS unsigned char* lds, const Gemm g, const Sched& S, const Epi& E) {
;     ...
;     f32x4 acc[2][2][4][2];
; #pragma unroll
;     for (int a = 0; a < 2; ++a)
; #pragma unroll
;         for (int b = 0; b < 2; ++b)
; #pragma unroll
;             for (int m = 0; m < 4; ++m)
; #pragma unroll
;                 for (int n = 0; n < 2; ++n) acc[a][b][m][n] = (f32x4){0.f, 0.f, 0.f, 0.f};
;     bf16x8 At[4][2], B0[2][2], B1[2][2];
;     const char* cA = (const char*)g.A + (size_t)cur.pm * tstep + (size_t)cur.seg * K * 2; const char* cB = (const char*)g.Bt + (size_t)cur.pn * tstepB + (size_t)cur.seg * K * 2;
;     if constexpr (SP2) {
;         PG8_STAGE(PG8_SB(0, 0), cB, voffB); PG8_STAGE(PG8_SB(0, 1), cB + hstepB, voffB); PG8_STAGE(PG8_SA(0, 0), cA, voffA); PG8_STAGE(PG8_SA(0, 1), cA + hstep, voffA);
;         if (wr == 1) PG8_BAR;
;         PG8_WAIT_V(2); PG8_BAR;
;         PG8_STAGE(PG8_SB(1, 0), cB + kstep, voffB); PG8_STAGE(PG8_SA(1, 0), cA + kstep, voffA); PG8_STAGE(PG8_SB(1, 1), cB + hstepB + kstep, voffB);
;         PG8_WAIT_V(6); PG8_BAR;
;     } else {
;         PG8_STAGE(PG8_SB(0, 0), cB, voffB); PG8_STAGE(PG8_SA(0, 0), cA, voffA); PG8_STAGE(PG8_SB(0, 1), cB + hstepB, voffB); PG8_STAGE(PG8_SA(0, 1), cA + hstep, voffA);
;         if (wr == 1) PG8_BAR;
;         PG8_WAIT_V(4); PG8_BAR;
;         PG8_STAGE(PG8_SB(1, 0), cB + kstep, voffB); PG8_STAGE(PG8_SA(1, 0), cA + kstep, voffA); PG8_STAGE(PG8_SB(1, 1), cB + hstepB + kstep, voffB);
;         PG8_WAIT_V(6); PG8_BAR;
;     }
;     for (;;) {
;         const bool has_next = S.next(ui + 1, nxt);
;         const char* nA = has_next ? (const char*)g.A + (size_t)nxt.pm * tstep + (size_t)nxt.seg * K * 2 : cA; const char* nB = has_next ? (const char*)g.Bt + (size_t)nxt.pn * tstepB + (size_t)nxt.seg * K * 2 : cB;
;         for (int t = 0; t < nt; t += 2) {
;             const bool last = (t == nt - 2);
;             const char* a1 = cA + (size_t)(t + 1) * kstep;
;             const char* a2 = last ? nA : cA + (size_t)(t + 2) * kstep; const char* b2 = last ? nB : cB + (size_t)(t + 2) * kstep;
;             const char* a3 = a2 + kstep; const char* b3 = b2 + kstep;
.LBB0_645:
	s_ashr_i32 s49, s48, 31
	s_lshl_b64 s[30:31], s[48:49], 19
	s_add_u32 s56, s86, s30
	s_addc_u32 s57, s87, s31
	s_and_b64 s[30:31], s[74:75], exec
	s_cselect_b32 s49, s57, s71
	s_cselect_b32 vcc_lo, s56, s70
	s_ashr_i32 s51, s50, 31
	s_lshl_b64 s[30:31], s[50:51], 19
	s_add_u32 s66, s92, s30
	s_addc_u32 s67, s93, s31
	s_and_b64 s[30:31], s[74:75], exec
	s_cselect_b32 s51, s67, s73
	s_cselect_b32 vcc_hi, s66, s72
	s_add_u32 s70, s70, 0x40080
	s_addc_u32 s71, s71, 0
	s_add_u32 s30, s72, 0x100
	v_mov_b32_e32 v2, 0
	s_addc_u32 s31, s73, 0
	s_mov_b32 s34, -2
	s_waitcnt lgkmcnt(0)
	v_mov_b32_e32 v3, v2
	v_mov_b32_e32 v4, v2
	v_mov_b32_e32 v5, v2
	v_mov_b32_e32 v6, v2
	v_mov_b32_e32 v7, v2
	v_mov_b32_e32 v8, v2
	v_mov_b32_e32 v9, v2
	v_mov_b32_e32 v18, v2
	v_mov_b32_e32 v19, v2
	v_mov_b32_e32 v20, v2
	v_mov_b32_e32 v21, v2
	v_mov_b32_e32 v22, v2
	v_mov_b32_e32 v23, v2
	v_mov_b32_e32 v24, v2
	v_mov_b32_e32 v25, v2
	v_mov_b32_e32 v34, v2
	v_mov_b32_e32 v35, v2
	v_mov_b32_e32 v36, v2
	v_mov_b32_e32 v37, v2
	v_mov_b32_e32 v38, v2
	v_mov_b32_e32 v39, v2
	v_mov_b32_e32 v40, v2
	v_mov_b32_e32 v41, v2
	v_mov_b32_e32 v50, v2
	v_mov_b32_e32 v51, v2
	v_mov_b32_e32 v52, v2
	v_mov_b32_e32 v53, v2
	v_mov_b32_e32 v54, v2
	v_mov_b32_e32 v55, v2
	v_mov_b32_e32 v56, v2
	v_mov_b32_e32 v57, v2
	v_mov_b32_e32 v10, v2
	v_mov_b32_e32 v11, v2
	v_mov_b32_e32 v12, v2
	v_mov_b32_e32 v13, v2
	v_mov_b32_e32 v14, v2
	v_mov_b32_e32 v15, v2
	v_mov_b32_e32 v16, v2
	v_mov_b32_e32 v17, v2
	v_mov_b32_e32 v26, v2
	v_mov_b32_e32 v27, v2
	v_mov_b32_e32 v28, v2
	v_mov_b32_e32 v29, v2
	v_mov_b32_e32 v30, v2
	v_mov_b32_e32 v31, v2
	v_mov_b32_e32 v32, v2
	v_mov_b32_e32 v33, v2
	v_mov_b32_e32 v42, v2
	v_mov_b32_e32 v43, v2
	v_mov_b32_e32 v44, v2
	v_mov_b32_e32 v45, v2
	v_mov_b32_e32 v46, v2
	v_mov_b32_e32 v47, v2
	v_mov_b32_e32 v48, v2
	v_mov_b32_e32 v49, v2
	v_mov_b32_e32 v58, v2
	v_mov_b32_e32 v59, v2
	v_mov_b32_e32 v60, v2
	v_mov_b32_e32 v61, v2
	v_mov_b32_e32 v62, v2
	v_mov_b32_e32 v63, v2
	v_mov_b32_e32 v64, v2
	v_mov_b32_e32 v65, v2
	v_mov_b32_e32 v68, v2
	v_mov_b32_e32 v69, v2
	v_mov_b32_e32 v70, v2
	v_mov_b32_e32 v71, v2
	v_mov_b32_e32 v72, v2
	v_mov_b32_e32 v73, v2
	v_mov_b32_e32 v74, v2
	v_mov_b32_e32 v75, v2
	v_mov_b32_e32 v84, v2
	v_mov_b32_e32 v85, v2
	v_mov_b32_e32 v86, v2
	v_mov_b32_e32 v87, v2
	v_mov_b32_e32 v88, v2
	v_mov_b32_e32 v89, v2
	v_mov_b32_e32 v90, v2
	v_mov_b32_e32 v91, v2
	v_mov_b32_e32 v100, v2
	v_mov_b32_e32 v101, v2
	v_mov_b32_e32 v102, v2
	v_mov_b32_e32 v103, v2
	v_mov_b32_e32 v104, v2
	v_mov_b32_e32 v105, v2
	v_mov_b32_e32 v106, v2
	v_mov_b32_e32 v107, v2
	v_mov_b32_e32 v116, v2
	v_mov_b32_e32 v117, v2
	v_mov_b32_e32 v118, v2
	v_mov_b32_e32 v119, v2
	v_mov_b32_e32 v120, v2
	v_mov_b32_e32 v121, v2
	v_mov_b32_e32 v122, v2
	v_mov_b32_e32 v123, v2
	v_mov_b32_e32 v76, v2
	v_mov_b32_e32 v77, v2
	v_mov_b32_e32 v78, v2
	v_mov_b32_e32 v79, v2
	v_mov_b32_e32 v80, v2
	v_mov_b32_e32 v81, v2
	v_mov_b32_e32 v82, v2
	v_mov_b32_e32 v83, v2
	v_mov_b32_e32 v92, v2
	v_mov_b32_e32 v93, v2
	v_mov_b32_e32 v94, v2
	v_mov_b32_e32 v95, v2
	v_mov_b32_e32 v96, v2
	v_mov_b32_e32 v97, v2
	v_mov_b32_e32 v98, v2
	v_mov_b32_e32 v99, v2
	v_mov_b32_e32 v108, v2
	v_mov_b32_e32 v109, v2
	v_mov_b32_e32 v110, v2
	v_mov_b32_e32 v111, v2
	v_mov_b32_e32 v112, v2
	v_mov_b32_e32 v113, v2
	v_mov_b32_e32 v114, v2
	v_mov_b32_e32 v115, v2
	v_mov_b32_e32 v124, v2
	v_mov_b32_e32 v125, v2
	v_mov_b32_e32 v126, v2
	v_mov_b32_e32 v127, v2
	v_mov_b32_e32 v128, v2
	v_mov_b32_e32 v129, v2
	v_mov_b32_e32 v130, v2
	v_mov_b32_e32 v131, v2
	.p2align 6

; #define PG8_WAIT_V(n) asm volatile("s_waitcnt vmcnt(" #n ")" ::: "memory")
; #define PG8_BAR __builtin_amdgcn_s_barrier()
; template <class Epi, class Sched, bool ALIGN_EPI = false, bool SP2 = false>
; __device__ __forceinline__ void gemm_phase(PG8_LAS unsigned char* lds, const Gemm g, const Sched& S, const Epi& E) {
;     ...
;     f32x4 acc[2][2][4][2];
; #pragma unroll
;     for (int a = 0; a < 2; ++a)
; #pragma unroll
;         for (int b = 0; b < 2; ++b)
; #pragma unroll
;             for (int m = 0; m < 4; ++m)
; #pragma unroll
;                 for (int n = 0; n < 2; ++n) acc[a][b][m][n] = (f32x4){0.f, 0.f, 0.f, 0.f};
;     bf16x8 At[4][2], B0[2][2], B1[2][2];
;     const char* cA = (const char*)g.A + (size_t)cur.pm * tstep + (size_t)cur.seg * K * 2; const char* cB = (const char*)g.Bt + (size_t)cur.pn * tstepB + (size_t)cur.seg * K * 2;
;     if constexpr (SP2) {
;         PG8_STAGE(PG8_SB(0, 0), cB, voffB); PG8_STAGE(PG8_SB(0, 1), cB + hstepB, voffB); PG8_STAGE(PG8_SA(0, 0), cA, voffA); PG8_STAGE(PG8_SA(0, 1), cA + hstep, voffA);
;         if (wr == 1) PG8_BAR;
;         PG8_WAIT_V(2); PG8_BAR;
;         PG8_STAGE(PG8_SB(1, 0), cB + kstep, voffB); PG8_STAGE(PG8_SA(1, 0), cA + kstep, voffA); PG8_STAGE(PG8_SB(1, 1), cB + hstepB + kstep, voffB);
;         PG8_WAIT_V(6); PG8_BAR;
;     } else {
;         PG8_STAGE(PG8_SB(0, 0), cB, voffB); PG8_STAGE(PG8_SA(0, 0), cA, voffA); PG8_STAGE(PG8_SB(0, 1), cB + hstepB, voffB); PG8_STAGE(PG8_SA(0, 1), cA + hstep, voffA);
;         if (wr == 1) PG8_BAR;
;         PG8_WAIT_V(4); PG8_BAR;
;         PG8_STAGE(PG8_SB(1, 0), cB + kstep, voffB); PG8_STAGE(PG8_SA(1, 0), cA + kstep, voffA); PG8_STAGE(PG8_SB(1, 1), cB + hstepB + kstep, voffB);
;         PG8_WAIT_V(6); PG8_BAR;
;     }
;     for (;;) {
;         const bool has_next = S.next(ui + 1, nxt);
;         const char* nA = has_next ? (const char*)g.A + (size_t)nxt.pm * tstep + (size_t)nxt.seg * K * 2 : cA; const char* nB = has_next ? (const char*)g.Bt + (size_t)nxt.pn * tstepB + (size_t)nxt.seg * K * 2 : cB;
;         for (int t = 0; t < nt; t += 2) {
;             const bool last = (t == nt - 2);
;             const char* a1 = cA + (size_t)(t + 1) * kstep;
;             const char* a2 = last ? nA : cA + (size_t)(t + 2) * kstep; const char* b2 = last ? nB : cB + (size_t)(t + 2) * kstep;
;             const char* a3 = a2 + kstep; const char* b3 = b2 + kstep;
.LBB0_781:
	s_ashr_i32 s47, s46, 31
	s_lshl_b64 s[30:31], s[46:47], 19
	s_add_u32 s56, s90, s30
	s_addc_u32 s57, s91, s31
	s_and_b64 s[30:31], s[50:51], exec
	s_cselect_b32 s47, s57, s63
	s_cselect_b32 s73, s56, s62
	s_ashr_i32 s49, s48, 31
	s_lshl_b64 s[30:31], s[48:49], 19
	s_add_u32 s60, s58, s30
	s_addc_u32 s61, s59, s31
	s_and_b64 s[30:31], s[50:51], exec
	s_cselect_b32 s49, s61, s67
	s_cselect_b32 s74, s60, s66
	s_add_u32 s62, s62, 0x40080
	s_addc_u32 s63, s63, 0
	s_add_u32 s30, s66, 0x100
	v_mov_b32_e32 v2, 0
	s_addc_u32 s31, s67, 0
	s_mov_b32 s34, -2
	v_mov_b32_e32 v3, v2
	v_mov_b32_e32 v4, v2
	v_mov_b32_e32 v5, v2
	v_mov_b32_e32 v10, v2
	v_mov_b32_e32 v11, v2
	v_mov_b32_e32 v12, v2
	v_mov_b32_e32 v13, v2
	v_mov_b32_e32 v18, v2
	v_mov_b32_e32 v19, v2
	v_mov_b32_e32 v20, v2
	v_mov_b32_e32 v21, v2
	v_mov_b32_e32 v26, v2
	v_mov_b32_e32 v27, v2
	v_mov_b32_e32 v28, v2
	v_mov_b32_e32 v29, v2
	v_mov_b32_e32 v34, v2
	v_mov_b32_e32 v35, v2
	v_mov_b32_e32 v36, v2
	v_mov_b32_e32 v37, v2
	v_mov_b32_e32 v42, v2
	v_mov_b32_e32 v43, v2
	v_mov_b32_e32 v44, v2
	v_mov_b32_e32 v45, v2
	v_mov_b32_e32 v50, v2
	v_mov_b32_e32 v51, v2
	v_mov_b32_e32 v52, v2
	v_mov_b32_e32 v53, v2
	v_mov_b32_e32 v58, v2
	v_mov_b32_e32 v59, v2
	v_mov_b32_e32 v60, v2
	v_mov_b32_e32 v61, v2
	v_mov_b32_e32 v6, v2
	v_mov_b32_e32 v7, v2
	v_mov_b32_e32 v8, v2
	v_mov_b32_e32 v9, v2
	v_mov_b32_e32 v14, v2
	v_mov_b32_e32 v15, v2
	v_mov_b32_e32 v16, v2
	v_mov_b32_e32 v17, v2
	v_mov_b32_e32 v22, v2
	v_mov_b32_e32 v23, v2
	v_mov_b32_e32 v24, v2
	v_mov_b32_e32 v25, v2
	v_mov_b32_e32 v30, v2
	v_mov_b32_e32 v31, v2
	v_mov_b32_e32 v32, v2
	v_mov_b32_e32 v33, v2
	v_mov_b32_e32 v38, v2
	v_mov_b32_e32 v39, v2
	v_mov_b32_e32 v40, v2
	v_mov_b32_e32 v41, v2
	v_mov_b32_e32 v46, v2
	v_mov_b32_e32 v47, v2
	v_mov_b32_e32 v48, v2
	v_mov_b32_e32 v49, v2
	v_mov_b32_e32 v54, v2
	v_mov_b32_e32 v55, v2
	v_mov_b32_e32 v56, v2
	v_mov_b32_e32 v57, v2
	v_mov_b32_e32 v62, v2
	v_mov_b32_e32 v63, v2
	v_mov_b32_e32 v64, v2
	v_mov_b32_e32 v65, v2
	v_mov_b32_e32 v68, v2
	v_mov_b32_e32 v69, v2
	v_mov_b32_e32 v70, v2
	v_mov_b32_e32 v71, v2
	v_mov_b32_e32 v76, v2
	v_mov_b32_e32 v77, v2
	v_mov_b32_e32 v78, v2
	v_mov_b32_e32 v79, v2
	v_mov_b32_e32 v84, v2
	v_mov_b32_e32 v85, v2
	v_mov_b32_e32 v86, v2
	v_mov_b32_e32 v87, v2
	v_mov_b32_e32 v92, v2
	v_mov_b32_e32 v93, v2
	v_mov_b32_e32 v94, v2
	v_mov_b32_e32 v95, v2
	v_mov_b32_e32 v100, v2
	v_mov_b32_e32 v101, v2
	v_mov_b32_e32 v102, v2
	v_mov_b32_e32 v103, v2
	v_mov_b32_e32 v108, v2
	v_mov_b32_e32 v109, v2
	v_mov_b32_e32 v110, v2
	v_mov_b32_e32 v111, v2
	v_mov_b32_e32 v116, v2
	v_mov_b32_e32 v117, v2
	v_mov_b32_e32 v118, v2
	v_mov_b32_e32 v119, v2
	v_mov_b32_e32 v124, v2
	v_mov_b32_e32 v125, v2
	v_mov_b32_e32 v126, v2
	v_mov_b32_e32 v127, v2
	v_mov_b32_e32 v72, v2
	v_mov_b32_e32 v73, v2
	v_mov_b32_e32 v74, v2
	v_mov_b32_e32 v75, v2
	v_mov_b32_e32 v80, v2
	v_mov_b32_e32 v81, v2
	v_mov_b32_e32 v82, v2
	v_mov_b32_e32 v83, v2
	v_mov_b32_e32 v88, v2
	v_mov_b32_e32 v89, v2
	v_mov_b32_e32 v90, v2
	v_mov_b32_e32 v91, v2
	v_mov_b32_e32 v96, v2
	v_mov_b32_e32 v97, v2
	v_mov_b32_e32 v98, v2
	v_mov_b32_e32 v99, v2
	v_mov_b32_e32 v104, v2
	v_mov_b32_e32 v105, v2
	v_mov_b32_e32 v106, v2
	v_mov_b32_e32 v107, v2
	v_mov_b32_e32 v112, v2
	v_mov_b32_e32 v113, v2
	v_mov_b32_e32 v114, v2
	v_mov_b32_e32 v115, v2
	v_mov_b32_e32 v120, v2
	v_mov_b32_e32 v121, v2
	v_mov_b32_e32 v122, v2
	v_mov_b32_e32 v123, v2
	v_mov_b32_e32 v128, v2
	v_mov_b32_e32 v129, v2
	v_mov_b32_e32 v130, v2
	v_mov_b32_e32 v131, v2
	.p2align 6

; #define PG8_WAIT_V(n) asm volatile("s_waitcnt vmcnt(" #n ")" ::: "memory")
; #define PG8_BAR __builtin_amdgcn_s_barrier()
; template <class Epi, class Sched, bool ALIGN_EPI = false, bool SP2 = false>
; __device__ __forceinline__ void gemm_phase(PG8_LAS unsigned char* lds, const Gemm g, const Sched& S, const Epi& E) {
;     ...
;     f32x4 acc[2][2][4][2];
; #pragma unroll
;     for (int a = 0; a < 2; ++a)
; #pragma unroll
;         for (int b = 0; b < 2; ++b)
; #pragma unroll
;             for (int m = 0; m < 4; ++m)
; #pragma unroll
;                 for (int n = 0; n < 2; ++n) acc[a][b][m][n] = (f32x4){0.f, 0.f, 0.f, 0.f};
;     bf16x8 At[4][2], B0[2][2], B1[2][2];
;     const char* cA = (const char*)g.A + (size_t)cur.pm * tstep + (size_t)cur.seg * K * 2; const char* cB = (const char*)g.Bt + (size_t)cur.pn * tstepB + (size_t)cur.seg * K * 2;
;     if constexpr (SP2) {
;         PG8_STAGE(PG8_SB(0, 0), cB, voffB); PG8_STAGE(PG8_SB(0, 1), cB + hstepB, voffB); PG8_STAGE(PG8_SA(0, 0), cA, voffA); PG8_STAGE(PG8_SA(0, 1), cA + hstep, voffA);
;         if (wr == 1) PG8_BAR;
;         PG8_WAIT_V(2); PG8_BAR;
;         PG8_STAGE(PG8_SB(1, 0), cB + kstep, voffB); PG8_STAGE(PG8_SA(1, 0), cA + kstep, voffA); PG8_STAGE(PG8_SB(1, 1), cB + hstepB + kstep, voffB);
;         PG8_WAIT_V(6); PG8_BAR;
;     } else {
;         PG8_STAGE(PG8_SB(0, 0), cB, voffB); PG8_STAGE(PG8_SA(0, 0), cA, voffA); PG8_STAGE(PG8_SB(0, 1), cB + hstepB, voffB); PG8_STAGE(PG8_SA(0, 1), cA + hstep, voffA);
;         if (wr == 1) PG8_BAR;
;         PG8_WAIT_V(4); PG8_BAR;
;         PG8_STAGE(PG8_SB(1, 0), cB + kstep, voffB); PG8_STAGE(PG8_SA(1, 0), cA + kstep, voffA); PG8_STAGE(PG8_SB(1, 1), cB + hstepB + kstep, voffB);
;         PG8_WAIT_V(6); PG8_BAR;
;     }
;     for (;;) {
;         const bool has_next = S.next(ui + 1, nxt);
;         const char* nA = has_next ? (const char*)g.A + (size_t)nxt.pm * tstep + (size_t)nxt.seg * K * 2 : cA; const char* nB = has_next ? (const char*)g.Bt + (size_t)nxt.pn * tstepB + (size_t)nxt.seg * K * 2 : cB;
;         for (int t = 0; t < nt; t += 2) {
;             const bool last = (t == nt - 2);
;             const char* a1 = cA + (size_t)(t + 1) * kstep;
;             const char* a2 = last ? nA : cA + (size_t)(t + 2) * kstep; const char* b2 = last ? nB : cB + (size_t)(t + 2) * kstep;
;             const char* a3 = a2 + kstep; const char* b3 = b2 + kstep;
.LBB0_911:
	s_add_u32 s30, s50, 0x100
	v_mov_b32_e32 v2, 0
	s_addc_u32 s31, s51, 0
	s_mov_b32 s34, -2
	s_waitcnt lgkmcnt(0)
	v_mov_b32_e32 v3, v2
	v_mov_b32_e32 v4, v2
	v_mov_b32_e32 v5, v2
	v_mov_b32_e32 v6, v2
	v_mov_b32_e32 v7, v2
	v_mov_b32_e32 v8, v2
	v_mov_b32_e32 v9, v2
	v_mov_b32_e32 v18, v2
	v_mov_b32_e32 v19, v2
	v_mov_b32_e32 v20, v2
	v_mov_b32_e32 v21, v2
	v_mov_b32_e32 v22, v2
	v_mov_b32_e32 v23, v2
	v_mov_b32_e32 v24, v2
	v_mov_b32_e32 v25, v2
	v_mov_b32_e32 v34, v2
	v_mov_b32_e32 v35, v2
	v_mov_b32_e32 v36, v2
	v_mov_b32_e32 v37, v2
	v_mov_b32_e32 v38, v2
	v_mov_b32_e32 v39, v2
	v_mov_b32_e32 v40, v2
	v_mov_b32_e32 v41, v2
	v_mov_b32_e32 v50, v2
	v_mov_b32_e32 v51, v2
	v_mov_b32_e32 v52, v2
	v_mov_b32_e32 v53, v2
	v_mov_b32_e32 v54, v2
	v_mov_b32_e32 v55, v2
	v_mov_b32_e32 v56, v2
	v_mov_b32_e32 v57, v2
	v_mov_b32_e32 v10, v2
	v_mov_b32_e32 v11, v2
	v_mov_b32_e32 v12, v2
	v_mov_b32_e32 v13, v2
	v_mov_b32_e32 v14, v2
	v_mov_b32_e32 v15, v2
	v_mov_b32_e32 v16, v2
	v_mov_b32_e32 v17, v2
	v_mov_b32_e32 v26, v2
	v_mov_b32_e32 v27, v2
	v_mov_b32_e32 v28, v2
	v_mov_b32_e32 v29, v2
	v_mov_b32_e32 v30, v2
	v_mov_b32_e32 v31, v2
	v_mov_b32_e32 v32, v2
	v_mov_b32_e32 v33, v2
	v_mov_b32_e32 v42, v2
	v_mov_b32_e32 v43, v2
	v_mov_b32_e32 v44, v2
	v_mov_b32_e32 v45, v2
	v_mov_b32_e32 v46, v2
	v_mov_b32_e32 v47, v2
	v_mov_b32_e32 v48, v2
	v_mov_b32_e32 v49, v2
	v_mov_b32_e32 v58, v2
	v_mov_b32_e32 v59, v2
	v_mov_b32_e32 v60, v2
	v_mov_b32_e32 v61, v2
	v_mov_b32_e32 v62, v2
	v_mov_b32_e32 v63, v2
	v_mov_b32_e32 v64, v2
	v_mov_b32_e32 v65, v2
	v_mov_b32_e32 v68, v2
	v_mov_b32_e32 v69, v2
	v_mov_b32_e32 v70, v2
	v_mov_b32_e32 v71, v2
	v_mov_b32_e32 v72, v2
	v_mov_b32_e32 v73, v2
	v_mov_b32_e32 v74, v2
	v_mov_b32_e32 v75, v2
	v_mov_b32_e32 v84, v2
	v_mov_b32_e32 v85, v2
	v_mov_b32_e32 v86, v2
	v_mov_b32_e32 v87, v2
	v_mov_b32_e32 v88, v2
	v_mov_b32_e32 v89, v2
	v_mov_b32_e32 v90, v2
	v_mov_b32_e32 v91, v2
	v_mov_b32_e32 v100, v2
	v_mov_b32_e32 v101, v2
	v_mov_b32_e32 v102, v2
	v_mov_b32_e32 v103, v2
	v_mov_b32_e32 v104, v2
	v_mov_b32_e32 v105, v2
	v_mov_b32_e32 v106, v2
	v_mov_b32_e32 v107, v2
	v_mov_b32_e32 v116, v2
	v_mov_b32_e32 v117, v2
	v_mov_b32_e32 v118, v2
	v_mov_b32_e32 v119, v2
	v_mov_b32_e32 v120, v2
	v_mov_b32_e32 v121, v2
	v_mov_b32_e32 v122, v2
	v_mov_b32_e32 v123, v2
	v_mov_b32_e32 v76, v2
	v_mov_b32_e32 v77, v2
	v_mov_b32_e32 v78, v2
	v_mov_b32_e32 v79, v2
	v_mov_b32_e32 v80, v2
	v_mov_b32_e32 v81, v2
	v_mov_b32_e32 v82, v2
	v_mov_b32_e32 v83, v2
	v_mov_b32_e32 v92, v2
	v_mov_b32_e32 v93, v2
	v_mov_b32_e32 v94, v2
	v_mov_b32_e32 v95, v2
	v_mov_b32_e32 v96, v2
	v_mov_b32_e32 v97, v2
	v_mov_b32_e32 v98, v2
	v_mov_b32_e32 v99, v2
	v_mov_b32_e32 v108, v2
	v_mov_b32_e32 v109, v2
	v_mov_b32_e32 v110, v2
	v_mov_b32_e32 v111, v2
	v_mov_b32_e32 v112, v2
	v_mov_b32_e32 v113, v2
	v_mov_b32_e32 v114, v2
	v_mov_b32_e32 v115, v2
	v_mov_b32_e32 v124, v2
	v_mov_b32_e32 v125, v2
	v_mov_b32_e32 v126, v2
	v_mov_b32_e32 v127, v2
	v_mov_b32_e32 v128, v2
	v_mov_b32_e32 v129, v2
	v_mov_b32_e32 v130, v2
	v_mov_b32_e32 v131, v2
	.p2align 6
